# P3 alpha: decay-scale vector LDS read issued first, its wait (lgkmcnt 5) no longer covers the five stage writes
# speedup vs baseline: 1.0317x; 1.0024x over previous
.LBB0_350:
	s_add_i32 s34, s47, 1
	s_and_b64 s[20:21], exec, s[38:39]
	s_cselect_b32 s48, s44, s34
	v_add_u32_e32 v116, 0x1e400, v143
	ds_read_b128 v[190:193], v116
	s_waitcnt vmcnt(18)
	ds_write_b128 v168, v[32:35] offset:44032
	s_waitcnt vmcnt(16)
	ds_write_b128 v168, v[36:39] offset:52736
	s_waitcnt vmcnt(15)
	ds_write_b128 v168, v[40:43] offset:61440
	s_waitcnt vmcnt(13)
	ds_write_b128 v166, v[44:47] offset:8704
	s_waitcnt vmcnt(17)
	ds_write_b128 v167, v[48:51]
	v_add_u32_e32 v32, s61, v138
	s_min_u32 s49, s44, 60
	s_waitcnt vmcnt(14)
	s_cmp_lg_u32 s69, 0
	s_cbranch_scc1 .Lev_skip_a
	ds_write_b128 v32, v[52:55]
.Lev_skip_a:
	s_add_i32 s34, s49, 3
	v_sub_u32_e64 v32, 60, s44 clamp
	s_and_b64 s[20:21], exec, s[38:39]
	v_readfirstlane_b32 s20, v32
	s_cselect_b32 s66, s34, s20
	s_lshl_b32 s34, s66, 13
	s_lshl_b32 s67, s66, 14
	s_add_u32 s20, s43, s67
	s_addc_u32 s21, s63, 0
	v_lshl_add_u64 v[36:37], s[20:21], 0, v[120:121]
	global_load_dwordx4 v[32:35], v120, s[20:21] nt
	v_add_co_u32_e64 v36, s[20:21], s60, v36
	v_lshl_add_u64 v[48:49], v[146:147], 0, s[34:35]
	global_load_dwordx4 v[48:51], v[48:49], off nt
	s_nop 0
	v_addc_co_u32_e64 v37, s[20:21], 0, v37, s[20:21]
	s_add_u32 s20, s64, s67
	s_addc_u32 s21, s65, 0
	v_lshl_add_u64 v[44:45], s[20:21], 0, v[120:121]
	global_load_dwordx4 v[36:39], v[36:37], off nt
	s_lshl_b32 s34, s66, 10
	global_load_dwordx4 v[40:43], v120, s[20:21] nt
	v_add_co_u32_e64 v44, s[20:21], s60, v44
	v_lshl_add_u64 v[52:53], v[148:149], 0, s[34:35]
	global_load_dwordx4 v[52:55], v[52:53], off
	s_nop 0
	v_addc_co_u32_e64 v45, s[20:21], 0, v45, s[20:21]
	global_load_dwordx4 v[44:47], v[44:45], off nt
	s_lshl_b32 s20, s49, 1
	s_add_i32 s34, s20, 4
	s_waitcnt vmcnt(16)
	v_mov_b32_e32 v214, v64
	v_mov_b32_e32 v215, v65
	v_mov_b32_e32 v216, v66
	v_mov_b32_e32 v217, v67
	v_lshl_add_u64 v[64:65], v[144:145], 0, s[34:35]
	s_add_i32 s34, 0, 0x1e400
	v_mov_b32_e32 v198, v56
	v_mov_b32_e32 v199, v57
	v_mov_b32_e32 v200, v58
	v_mov_b32_e32 v201, v59
	v_mov_b32_e32 v202, v60
	v_mov_b32_e32 v203, v61
	v_mov_b32_e32 v204, v62
	v_mov_b32_e32 v205, v63
	s_waitcnt vmcnt(15)
	v_mov_b32_e32 v242, v68
	v_mov_b32_e32 v243, v69
	v_mov_b32_e32 v244, v70
	v_mov_b32_e32 v245, v71
	v_and_b32_e32 v66, 0xfff, v64
	v_cmp_ne_u32_e64 s[20:21], 0, v66
	v_add_u32_e32 v185, 0, v143
	v_add_u32_e32 v116, 0x1e600, v185
	s_waitcnt lgkmcnt(5)
	v_pk_mul_f32 v[192:193], v[98:99], v[192:193]
	v_pk_mul_f32 v[190:191], v[96:97], v[190:191]
	v_pk_mul_f32 v[98:99], v[102:103], v[192:193]
	v_pk_mul_f32 v[96:97], v[100:101], v[190:191]
	v_cndmask_b32_e64 v56, 0, 1, s[20:21]
	v_cvt_pk_bf16_f32 v100, v96, v97
	v_cvt_pk_bf16_f32 v101, v98, v99
	v_sub_co_u32_e64 v56, s[20:21], v64, v56
	ds_read_b128 v[116:119], v116
	ds_write_b64 v182, v[100:101]
	v_pk_mul_f32 v[100:101], v[104:105], v[190:191]
	v_pk_mul_f32 v[102:103], v[106:107], v[192:193]
	v_subbrev_co_u32_e64 v57, s[20:21], 0, v65, s[20:21]
	v_cvt_pk_bf16_f32 v104, v100, v101
	v_cvt_pk_bf16_f32 v105, v102, v103
	v_cmp_ne_u32_e64 s[20:21], s62, v66
	ds_write_b64 v182, v[104:105] offset:4352
	v_pk_mul_f32 v[104:105], v[108:109], v[190:191]
	v_pk_mul_f32 v[106:107], v[110:111], v[192:193]
	v_cndmask_b32_e64 v66, 0, 1, s[20:21]
	v_mov_b32_e32 v67, s35
	v_cvt_pk_bf16_f32 v108, v104, v105
	v_cvt_pk_bf16_f32 v109, v106, v107
	v_lshlrev_b64 v[68:69], 11, v[64:65]
	v_lshl_add_u64 v[64:65], v[64:65], 0, v[66:67]
	ds_write_b64 v182, v[108:109] offset:8704
	v_pk_mul_f32 v[108:109], v[112:113], v[190:191]
	v_pk_mul_f32 v[110:111], v[114:115], v[192:193]
	v_lshlrev_b64 v[56:57], 11, v[56:57]
	v_lshlrev_b64 v[64:65], 11, v[64:65]
	v_cvt_pk_bf16_f32 v112, v108, v109
	v_cvt_pk_bf16_f32 v113, v110, v111
	v_lshl_add_u64 v[56:57], v[134:135], 0, v[56:57]
	v_lshl_add_u64 v[60:61], v[134:135], 0, v[68:69]
	v_lshl_add_u64 v[64:65], v[134:135], 0, v[64:65]
	v_lshl_add_u64 v[68:69], v[136:137], 0, v[68:69]
	ds_write_b64 v182, v[112:113] offset:13056
	global_load_dwordx4 v[56:59], v[56:57], off
	s_lshl_b32 s48, s48, 6
	global_load_dwordx4 v[60:63], v[60:61], off
	s_nop 0
	global_load_dwordx4 v[64:67], v[64:65], off
	s_nop 0
	global_load_dwordx4 v[68:71], v[68:69], off nt
	s_waitcnt lgkmcnt(0)
	s_barrier
	ds_read_b128 v[218:221], v183
	ds_read_b128 v[230:233], v183 offset:64
	v_and_b32_e32 v250, 0xfff, v184
	v_cmp_ne_u32_e64 s[20:21], 0, v250
	v_add_u32_e32 v184, 4, v184
	s_nop 0
	v_cndmask_b32_e64 v198, 0, v198, s[20:21]
	v_cndmask_b32_e64 v199, 0, v199, s[20:21]
	v_cndmask_b32_e64 v200, 0, v200, s[20:21]
	v_cndmask_b32_e64 v201, 0, v201, s[20:21]
	v_cmp_ne_u32_e64 s[20:21], s62, v250
	v_lshlrev_b32_e32 v246, 16, v202
	v_and_b32_e32 v247, 0xffff0000, v202
	v_cndmask_b32_e64 v214, 0, v214, s[20:21]
	v_cndmask_b32_e64 v215, 0, v215, s[20:21]
	v_cndmask_b32_e64 v216, 0, v216, s[20:21]
	v_cndmask_b32_e64 v217, 0, v217, s[20:21]
	v_pk_mul_f32 v[246:247], v[8:9], v[246:247]
	v_lshlrev_b32_e32 v248, 16, v198
	v_and_b32_e32 v249, 0xffff0000, v198
	v_pk_fma_f32 v[246:247], v[0:1], v[248:249], v[246:247]
	v_lshlrev_b32_e32 v248, 16, v214
	v_and_b32_e32 v249, 0xffff0000, v214
	v_pk_fma_f32 v[246:247], v[16:17], v[248:249], v[246:247]
	v_pk_add_f32 v[246:247], v[24:25], v[246:247]
	v_lshlrev_b32_e32 v248, 16, v242
	v_and_b32_e32 v249, 0xffff0000, v242
	v_pk_mul_f32 v[246:247], v[246:247], v[248:249]
	v_cvt_pk_bf16_f32 v198, v246, v247
	v_lshlrev_b32_e32 v246, 16, v203
	v_and_b32_e32 v247, 0xffff0000, v203
	v_pk_mul_f32 v[246:247], v[10:11], v[246:247]
	v_lshlrev_b32_e32 v248, 16, v199
	v_and_b32_e32 v249, 0xffff0000, v199
	v_pk_fma_f32 v[246:247], v[2:3], v[248:249], v[246:247]
	v_lshlrev_b32_e32 v248, 16, v215
	v_and_b32_e32 v249, 0xffff0000, v215
	v_pk_fma_f32 v[246:247], v[18:19], v[248:249], v[246:247]
	v_pk_add_f32 v[246:247], v[26:27], v[246:247]
	v_lshlrev_b32_e32 v248, 16, v243
	v_and_b32_e32 v249, 0xffff0000, v243
	v_pk_mul_f32 v[246:247], v[246:247], v[248:249]
	v_cvt_pk_bf16_f32 v199, v246, v247
	v_lshlrev_b32_e32 v246, 16, v204
	v_and_b32_e32 v247, 0xffff0000, v204
	v_pk_mul_f32 v[246:247], v[12:13], v[246:247]
	v_lshlrev_b32_e32 v248, 16, v200
	v_and_b32_e32 v249, 0xffff0000, v200
	v_pk_fma_f32 v[246:247], v[4:5], v[248:249], v[246:247]
	v_lshlrev_b32_e32 v248, 16, v216
	v_and_b32_e32 v249, 0xffff0000, v216
	v_pk_fma_f32 v[246:247], v[20:21], v[248:249], v[246:247]
	v_pk_add_f32 v[246:247], v[28:29], v[246:247]
	v_lshlrev_b32_e32 v248, 16, v244
	v_and_b32_e32 v249, 0xffff0000, v244
	v_pk_mul_f32 v[246:247], v[246:247], v[248:249]
	v_cvt_pk_bf16_f32 v200, v246, v247
	v_lshlrev_b32_e32 v246, 16, v205
	v_and_b32_e32 v247, 0xffff0000, v205
	v_pk_mul_f32 v[246:247], v[14:15], v[246:247]
	v_lshlrev_b32_e32 v248, 16, v201
	v_and_b32_e32 v249, 0xffff0000, v201
	v_pk_fma_f32 v[246:247], v[6:7], v[248:249], v[246:247]
	v_lshlrev_b32_e32 v248, 16, v217
	v_and_b32_e32 v249, 0xffff0000, v217
	v_pk_fma_f32 v[246:247], v[22:23], v[248:249], v[246:247]
	v_pk_add_f32 v[246:247], v[30:31], v[246:247]
	v_lshlrev_b32_e32 v248, 16, v245
	v_and_b32_e32 v249, 0xffff0000, v245
	v_pk_mul_f32 v[246:247], v[246:247], v[248:249]
	v_cvt_pk_bf16_f32 v201, v246, v247
	global_store_dwordx4 v[152:153], v[198:201], off
	s_nop 1
	ds_read_b128 v[242:245], v183 offset:128
	s_waitcnt lgkmcnt(2)
	v_mfma_f32_16x16x32_bf16 v[198:201], v[218:221], v[122:125], 0
	v_mfma_f32_16x16x32_bf16 v[202:205], v[218:221], v[126:129], 0
	ds_read_b128 v[218:221], v183 offset:192
	s_waitcnt lgkmcnt(2)
	v_mfma_f32_16x16x32_bf16 v[198:201], v[230:233], v[130:133], v[198:201]
	v_mfma_f32_16x16x32_bf16 v[202:205], v[230:233], v[160:163], v[202:205]
	ds_read_b128 v[230:233], v170 offset:61440
	ds_read_b128 v[122:125], v171 offset:44032
	ds_read_b128 v[126:129], v172 offset:44032
	s_waitcnt lgkmcnt(4)
	v_mfma_f32_16x16x32_bf16 v[198:201], v[242:245], v[210:213], v[198:201]
	v_mfma_f32_16x16x32_bf16 v[202:205], v[242:245], v[154:157], v[202:205]
	ds_read_b128 v[242:245], v170 offset:61504
	ds_read_b128 v[130:133], v171 offset:44096
	ds_read_b128 v[160:163], v172 offset:44096
	s_waitcnt lgkmcnt(6)
	v_mfma_f32_16x16x32_bf16 v[198:201], v[218:221], v[206:209], v[198:201]
	v_mfma_f32_16x16x32_bf16 v[202:205], v[218:221], v[174:177], v[202:205]
	ds_read_b128 v[218:221], v170 offset:61568
	ds_read_b128 v[210:213], v171 offset:44160
	ds_read_b128 v[154:157], v172 offset:44160
	s_waitcnt lgkmcnt(6)
	v_mfma_f32_16x16x32_bf16 v[190:193], v[230:233], v[122:125], 0
	v_mfma_f32_16x16x32_bf16 v[194:197], v[230:233], v[126:129], 0
	ds_read_b128 v[230:233], v170 offset:61632
	ds_read_b128 v[206:209], v171 offset:44224
	ds_read_b128 v[174:177], v172 offset:44224
	s_waitcnt lgkmcnt(6)
	v_mfma_f32_16x16x32_bf16 v[190:193], v[242:245], v[130:133], v[190:193]
	v_mfma_f32_16x16x32_bf16 v[194:197], v[242:245], v[160:163], v[194:197]
	ds_read_b64_tr_b16 v[242:243], v139
	ds_read_b64_tr_b16 v[244:245], v139 offset:512
	ds_read_b128 v[246:249], v142
	ds_read_b128 v[250:253], v159
	s_waitcnt lgkmcnt(7)
	v_mfma_f32_16x16x32_bf16 v[190:193], v[218:221], v[210:213], v[190:193]
	v_mfma_f32_16x16x32_bf16 v[194:197], v[218:221], v[154:157], v[194:197]
	ds_read_b64_tr_b16 v[218:219], v139 offset:4096
	ds_read_b64_tr_b16 v[220:221], v139 offset:4608
	ds_read_b128 v[222:225], v142 offset:64
	ds_read_b128 v[226:229], v159 offset:64
	s_waitcnt lgkmcnt(8)
	v_mfma_f32_16x16x32_bf16 v[190:193], v[230:233], v[206:209], v[190:193]
	v_mfma_f32_16x16x32_bf16 v[194:197], v[230:233], v[174:177], v[194:197]
	s_nop 6
	v_cndmask_b32_e32 v190, 0, v190, vcc
	v_cndmask_b32_e64 v191, 0, v191, s[6:7]
	v_cndmask_b32_e64 v192, 0, v192, s[8:9]
	v_cndmask_b32_e64 v193, 0, v193, s[10:11]
	v_cvt_pk_bf16_f32 v190, v190, v191
	v_cvt_pk_bf16_f32 v191, v192, v193
	v_cndmask_b32_e64 v194, 0, v194, s[12:13]
	v_cndmask_b32_e64 v195, 0, v195, s[14:15]
	v_cndmask_b32_e64 v196, 0, v196, s[16:17]
	v_cndmask_b32_e64 v197, 0, v197, s[18:19]
	v_cvt_pk_bf16_f32 v194, v194, v195
	v_cvt_pk_bf16_f32 v195, v196, v197
	ds_write_b64 v164, v[190:191] offset:9216
	ds_write_b64 v180, v[194:195] offset:9216
	ds_read_b64_tr_b16 v[190:191], v178 offset:17408
	ds_read_b64_tr_b16 v[192:193], v178 offset:18496
	ds_read_b64_tr_b16 v[194:195], v178 offset:26112
	ds_read_b64_tr_b16 v[196:197], v178 offset:27200
	s_waitcnt lgkmcnt(10)
	v_mfma_f32_16x16x32_bf16 v[198:201], v[242:245], v[246:249], v[198:201]
	v_mfma_f32_16x16x32_bf16 v[202:205], v[242:245], v[250:253], v[202:205]
	ds_read_b64_tr_b16 v[242:243], v186
	ds_read_b64_tr_b16 v[244:245], v186 offset:512
	ds_read_b64_tr_b16 v[246:247], v187
	ds_read_b64_tr_b16 v[248:249], v187 offset:512
	s_waitcnt lgkmcnt(10)
	v_mfma_f32_16x16x32_bf16 v[198:201], v[218:221], v[222:225], v[198:201]
	v_mfma_f32_16x16x32_bf16 v[202:205], v[218:221], v[226:229], v[202:205]
	ds_read_b64_tr_b16 v[218:219], v188
	ds_read_b64_tr_b16 v[220:221], v188 offset:512
	ds_read_b64_tr_b16 v[222:223], v189
	ds_read_b64_tr_b16 v[224:225], v189 offset:512
	s_waitcnt lgkmcnt(8)
	ds_read_b64_tr_b16 v[230:231], v186 offset:4096
	ds_read_b64_tr_b16 v[232:233], v186 offset:4608
	ds_read_b64_tr_b16 v[234:235], v187 offset:4096
	ds_read_b64_tr_b16 v[236:237], v187 offset:4608
	s_waitcnt lgkmcnt(8)
	v_mfma_f32_16x16x32_bf16 v[96:99], v[190:193], v[242:245], v[96:99]
	v_mfma_f32_16x16x32_bf16 v[100:103], v[190:193], v[246:249], v[100:103]
	ds_read_b64_tr_b16 v[242:243], v188 offset:4096
	ds_read_b64_tr_b16 v[244:245], v188 offset:4608
	ds_read_b64_tr_b16 v[246:247], v189 offset:4096
	ds_read_b64_tr_b16 v[248:249], v189 offset:4608
	v_cvt_pk_bf16_f32 v198, v198, v199
	v_cvt_pk_bf16_f32 v199, v200, v201
	v_cvt_pk_bf16_f32 v200, v202, v203
	v_cvt_pk_bf16_f32 v201, v204, v205
	v_add_u32_e32 v254, s48, v173
	v_mad_u64_u32 v[254:255], s[20:21], v254, s42, 0
	v_lshl_add_u64 v[254:255], v[254:255], 1, v[150:151]
	v_permlane16_swap_b32_e32 v198, v200
	v_permlane16_swap_b32_e32 v199, v201
	global_store_dwordx4 v[254:255], v[198:201], off
	s_waitcnt lgkmcnt(8)
	v_mfma_f32_16x16x32_bf16 v[104:107], v[190:193], v[218:221], v[104:107]
	v_mfma_f32_16x16x32_bf16 v[214:217], v[190:193], v[222:225], v[108:111]
	s_waitcnt lgkmcnt(4)
	v_mfma_f32_16x16x32_bf16 v[112:115], v[194:197], v[230:233], v[96:99]
	v_mfma_f32_16x16x32_bf16 v[108:111], v[194:197], v[234:237], v[100:103]
	s_waitcnt lgkmcnt(0)
	v_mfma_f32_16x16x32_bf16 v[104:107], v[194:197], v[242:245], v[104:107]
	v_mfma_f32_16x16x32_bf16 v[100:103], v[194:197], v[246:249], v[214:217]
	s_min_u32 s20, s44, 59
	s_waitcnt lgkmcnt(0)
	s_barrier
	v_add_u32_e32 v96, s61, v143
	ds_read_b128 v[222:225], v96
	s_waitcnt vmcnt(18)
	ds_write_b128 v168, v[72:75]
	s_waitcnt vmcnt(17)
	ds_write_b128 v168, v[80:83] offset:8704
	s_waitcnt vmcnt(15)
	ds_write_b128 v168, v[76:79] offset:17408
	s_waitcnt vmcnt(14)
	ds_write_b128 v168, v[84:87] offset:26112
	s_waitcnt vmcnt(16)
	ds_write_b128 v169, v[88:91] offset:34816
	v_add_u32_e32 v72, s34, v138
	s_add_i32 s34, s20, 4
	s_waitcnt vmcnt(13)
	s_cmp_lg_u32 s69, 0
	s_cbranch_scc1 .Lev_skip_b
	ds_write_b128 v72, v[92:95]
.Lev_skip_b:
	v_sub_u32_e64 v72, 59, s44 clamp
	s_and_b64 s[20:21], exec, s[38:39]
	v_readfirstlane_b32 s20, v72
	s_cselect_b32 s48, s34, s20
	s_lshl_b32 s34, s48, 13
	s_lshl_b32 s49, s48, 14
	s_add_u32 s20, s43, s49
	s_addc_u32 s21, s63, 0
	v_lshl_add_u64 v[76:77], s[20:21], 0, v[120:121]
	global_load_dwordx4 v[72:75], v120, s[20:21] nt
	v_add_co_u32_e64 v76, s[20:21], s60, v76
	s_waitcnt lgkmcnt(5)
	v_pk_mul_f32 v[118:119], v[118:119], v[224:225]
	v_addc_co_u32_e64 v77, s[20:21], 0, v77, s[20:21]
	v_pk_mul_f32 v[116:117], v[116:117], v[222:223]
	s_add_u32 s20, s64, s49
	v_pk_mul_f32 v[114:115], v[114:115], v[118:119]
	v_pk_mul_f32 v[112:113], v[112:113], v[116:117]
	s_addc_u32 s21, s65, 0
	v_add_u32_e32 v96, 0x1ea00, v185
	v_cvt_pk_bf16_f32 v222, v112, v113
	v_cvt_pk_bf16_f32 v223, v114, v115
	v_pk_mul_f32 v[110:111], v[110:111], v[118:119]
	v_pk_mul_f32 v[108:109], v[108:109], v[116:117]
	v_lshl_add_u64 v[84:85], s[20:21], 0, v[120:121]
	ds_read_b128 v[96:99], v96
	ds_write_b64 v182, v[222:223]
	v_cvt_pk_bf16_f32 v222, v108, v109
	v_cvt_pk_bf16_f32 v223, v110, v111
	v_pk_mul_f32 v[106:107], v[106:107], v[118:119]
	v_pk_mul_f32 v[104:105], v[104:105], v[116:117]
	v_pk_mul_f32 v[102:103], v[102:103], v[118:119]
	v_pk_mul_f32 v[100:101], v[100:101], v[116:117]
	global_load_dwordx4 v[80:83], v[76:77], off nt
	v_lshl_add_u64 v[88:89], v[146:147], 0, s[34:35]
	global_load_dwordx4 v[88:91], v[88:89], off nt
	global_load_dwordx4 v[76:79], v120, s[20:21] nt
	v_add_co_u32_e64 v84, s[20:21], s60, v84
	s_lshl_b32 s34, s48, 10
	ds_write_b64 v182, v[222:223] offset:4352
	v_cvt_pk_bf16_f32 v222, v104, v105
	v_cvt_pk_bf16_f32 v223, v106, v107
	v_cvt_pk_bf16_f32 v116, v100, v101
	v_cvt_pk_bf16_f32 v117, v102, v103
	v_addc_co_u32_e64 v85, s[20:21], 0, v85, s[20:21]
	global_load_dwordx4 v[84:87], v[84:85], off nt
	v_lshl_add_u64 v[92:93], v[148:149], 0, s[34:35]
	global_load_dwordx4 v[92:95], v[92:93], off
	ds_write_b64 v182, v[222:223] offset:8704
	ds_write_b64 v182, v[116:117] offset:13056
	s_waitcnt lgkmcnt(0)
	s_barrier
	ds_read_b128 v[218:221], v183
	ds_read_b128 v[230:233], v183 offset:64
	ds_read_b128 v[242:245], v183 offset:128
	s_add_i32 s34, s44, 1
	s_and_b64 s[20:21], exec, s[38:39]
	s_cselect_b32 s20, s34, s47
	s_lshl_b32 s34, s20, 6
	s_add_i32 s47, s47, -2
	v_lshl_add_u64 v[152:153], v[152:153], 0, s[36:37]
	s_waitcnt lgkmcnt(2)
	v_mfma_f32_16x16x32_bf16 v[198:201], v[218:221], v[122:125], 0
	v_mfma_f32_16x16x32_bf16 v[202:205], v[218:221], v[126:129], 0
	ds_read_b128 v[218:221], v183 offset:192
	s_waitcnt lgkmcnt(2)
	v_mfma_f32_16x16x32_bf16 v[198:201], v[230:233], v[130:133], v[198:201]
	v_mfma_f32_16x16x32_bf16 v[202:205], v[230:233], v[160:163], v[202:205]
	ds_read_b128 v[230:233], v170 offset:17408
	ds_read_b128 v[122:125], v171
	ds_read_b128 v[126:129], v172
	s_waitcnt lgkmcnt(4)
	v_mfma_f32_16x16x32_bf16 v[198:201], v[242:245], v[210:213], v[198:201]
	v_mfma_f32_16x16x32_bf16 v[202:205], v[242:245], v[154:157], v[202:205]
	ds_read_b128 v[242:245], v170 offset:17472
	ds_read_b128 v[130:133], v171 offset:64
	ds_read_b128 v[160:163], v172 offset:64
	s_waitcnt lgkmcnt(6)
	v_mfma_f32_16x16x32_bf16 v[198:201], v[218:221], v[206:209], v[198:201]
	v_mfma_f32_16x16x32_bf16 v[202:205], v[218:221], v[174:177], v[202:205]
	ds_read_b128 v[218:221], v170 offset:17536
	ds_read_b128 v[210:213], v171 offset:128
	ds_read_b128 v[154:157], v172 offset:128
	s_waitcnt lgkmcnt(6)
	v_mfma_f32_16x16x32_bf16 v[190:193], v[230:233], v[122:125], 0
	v_mfma_f32_16x16x32_bf16 v[194:197], v[230:233], v[126:129], 0
	ds_read_b128 v[230:233], v170 offset:17600
	ds_read_b128 v[206:209], v171 offset:192
	ds_read_b128 v[174:177], v172 offset:192
	s_waitcnt lgkmcnt(6)
	v_mfma_f32_16x16x32_bf16 v[190:193], v[242:245], v[130:133], v[190:193]
	v_mfma_f32_16x16x32_bf16 v[194:197], v[242:245], v[160:163], v[194:197]
	ds_read_b64_tr_b16 v[242:243], v139 offset:44032
	ds_read_b64_tr_b16 v[244:245], v139 offset:44544
	ds_read_b128 v[246:249], v142 offset:9216
	ds_read_b128 v[250:253], v159 offset:9216
	s_waitcnt lgkmcnt(7)
	v_mfma_f32_16x16x32_bf16 v[190:193], v[218:221], v[210:213], v[190:193]
	v_mfma_f32_16x16x32_bf16 v[194:197], v[218:221], v[154:157], v[194:197]
	ds_read_b64_tr_b16 v[218:219], v139 offset:48128
	ds_read_b64_tr_b16 v[220:221], v139 offset:48640
	ds_read_b128 v[222:225], v142 offset:9280
	ds_read_b128 v[226:229], v159 offset:9280
	s_waitcnt lgkmcnt(8)
	v_mfma_f32_16x16x32_bf16 v[190:193], v[230:233], v[206:209], v[190:193]
	v_mfma_f32_16x16x32_bf16 v[194:197], v[230:233], v[174:177], v[194:197]
	s_nop 6
	v_cndmask_b32_e32 v190, 0, v190, vcc
	v_cndmask_b32_e64 v191, 0, v191, s[6:7]
	v_cndmask_b32_e64 v192, 0, v192, s[8:9]
	v_cndmask_b32_e64 v193, 0, v193, s[10:11]
	v_cvt_pk_bf16_f32 v190, v190, v191
	v_cvt_pk_bf16_f32 v191, v192, v193
	v_cndmask_b32_e64 v194, 0, v194, s[12:13]
	v_cndmask_b32_e64 v195, 0, v195, s[14:15]
	v_cndmask_b32_e64 v196, 0, v196, s[16:17]
	v_cndmask_b32_e64 v197, 0, v197, s[18:19]
	v_cvt_pk_bf16_f32 v194, v194, v195
	v_cvt_pk_bf16_f32 v195, v196, v197
	ds_write_b64 v164, v[190:191]
	ds_write_b64 v180, v[194:195]
	ds_read_b64_tr_b16 v[190:191], v178 offset:61440
	ds_read_b64_tr_b16 v[192:193], v178 offset:62528
	ds_read_b64_tr_b16 v[194:195], v181 offset:8704
	ds_read_b64_tr_b16 v[196:197], v181 offset:9792
	s_waitcnt lgkmcnt(10)
	v_mfma_f32_16x16x32_bf16 v[198:201], v[242:245], v[246:249], v[198:201]
	v_mfma_f32_16x16x32_bf16 v[202:205], v[242:245], v[250:253], v[202:205]
	ds_read_b64_tr_b16 v[242:243], v186 offset:44032
	ds_read_b64_tr_b16 v[244:245], v186 offset:44544
	ds_read_b64_tr_b16 v[246:247], v187 offset:44032
	ds_read_b64_tr_b16 v[248:249], v187 offset:44544
	s_waitcnt lgkmcnt(10)
	v_mfma_f32_16x16x32_bf16 v[198:201], v[218:221], v[222:225], v[198:201]
	v_mfma_f32_16x16x32_bf16 v[202:205], v[218:221], v[226:229], v[202:205]
	ds_read_b64_tr_b16 v[218:219], v188 offset:44032
	ds_read_b64_tr_b16 v[220:221], v188 offset:44544
	ds_read_b64_tr_b16 v[222:223], v189 offset:44032
	ds_read_b64_tr_b16 v[224:225], v189 offset:44544
	s_waitcnt lgkmcnt(8)
	ds_read_b64_tr_b16 v[230:231], v186 offset:48128
	ds_read_b64_tr_b16 v[232:233], v186 offset:48640
	ds_read_b64_tr_b16 v[234:235], v187 offset:48128
	ds_read_b64_tr_b16 v[236:237], v187 offset:48640
	s_waitcnt lgkmcnt(8)
	v_mfma_f32_16x16x32_bf16 v[112:115], v[190:193], v[242:245], v[112:115]
	v_mfma_f32_16x16x32_bf16 v[108:111], v[190:193], v[246:249], v[108:111]
	ds_read_b64_tr_b16 v[242:243], v188 offset:48128
	ds_read_b64_tr_b16 v[244:245], v188 offset:48640
	ds_read_b64_tr_b16 v[246:247], v189 offset:48128
	ds_read_b64_tr_b16 v[248:249], v189 offset:48640
	v_cvt_pk_bf16_f32 v198, v198, v199
	v_cvt_pk_bf16_f32 v199, v200, v201
	v_cvt_pk_bf16_f32 v200, v202, v203
	v_cvt_pk_bf16_f32 v201, v204, v205
	v_add_u32_e32 v254, s34, v173
	v_mad_u64_u32 v[254:255], s[20:21], v254, s42, 0
	v_lshl_add_u64 v[254:255], v[254:255], 1, v[150:151]
	v_permlane16_swap_b32_e32 v198, v200
	v_permlane16_swap_b32_e32 v199, v201
	global_store_dwordx4 v[254:255], v[198:201], off
	s_waitcnt lgkmcnt(8)
	v_mfma_f32_16x16x32_bf16 v[214:217], v[190:193], v[218:221], v[104:107]
	v_mfma_f32_16x16x32_bf16 v[116:119], v[190:193], v[222:225], v[100:103]
	s_waitcnt lgkmcnt(4)
	v_mfma_f32_16x16x32_bf16 v[100:103], v[194:197], v[230:233], v[112:115]
	v_mfma_f32_16x16x32_bf16 v[104:107], v[194:197], v[234:237], v[108:111]
	s_waitcnt lgkmcnt(0)
	v_mfma_f32_16x16x32_bf16 v[108:111], v[194:197], v[242:245], v[214:217]
	v_mfma_f32_16x16x32_bf16 v[112:115], v[194:197], v[246:249], v[116:119]
	s_add_i32 s20, s44, 2
	s_cmp_lt_u32 s44, 62
	s_mov_b32 s44, s20
	s_waitcnt lgkmcnt(0)
	s_barrier
	s_cbranch_scc1 .LBB0_350
	s_add_i32 s30, s30, s28
	v_lshl_add_u64 v[140:141], v[140:141], 0, s[26:27]
	s_cmpk_lt_i32 s30, 0x100
	v_add_u32_e32 v165, s29, v165
	s_cbranch_scc1 .LBB0_344
